# attnB: one static s_setprio 1 for waves 4-7 across the main loop (reset before the epilogue)
# baseline (speedup 1.0000x reference)
; #define DMA_K(t, slot) do { _Pragma("unroll") for (int i_ = 0; i_ < 2; ++i_) __builtin_amdgcn_global_load_lds((const unsigned*)(ksrc[i_] + (size_t)(t) * 64 * DM), (LAS unsigned*)(lds3 + (slot) + (i_ * 8 + wid) * 1024), 16, 0, 0); } while (0)
; #define DMA_V(t, slot) do { _Pragma("unroll") for (int i_ = 0; i_ < 2; ++i_) __builtin_amdgcn_global_load_lds((const unsigned*)(vsrc[i_] + (size_t)(t) * 64 * DM), (LAS unsigned*)(lds3 + RING + (slot) + (i_ * 8 + wid) * 1024), 16, 0, 0); } while (0)
; __device__ __forceinline__ void attnB_unit(const bf16* Q, const bf16* __restrict__ K, const bf16* __restrict__ V, bf16* O, long rowbase, int seq, int h, int q0, float lam, char* lds, LAS unsigned char* lds3) {
;     ...
;     for (int i = 0; i < 2; ++i) { const int q = (i * 8 + wid) * 64 + lane;
;         { const int row = q >> 4, lc = (q & 15) ^ (row & 7); ksrc[i] = K + (size_t)(rowbase + row) * DM + h * 128 + lc * 8; }
;         { const int st = q >> 5, w = q & 31, k = (st >> 2) * 8 + (w >> 2), cc = (st & 3) * 32 + (w & 3) * 8;
;           vsrc[i] = V + (size_t)(rowbase + k) * DM + h * 128 + cc; } }
;     ...
;     DMA_K(0, 0); DMA_V(0, 0); DMA_K(1, SHM_KV);
;     const bf16* Qw = Q + (size_t)(rowbase + q0 + wq * 32 + r32) * DM + h * 128 + c * 64 + hi * 8;
; #pragma unroll
;     for (int d0 = 0; d0 < 4; ++d0) qr[d0] = *reinterpret_cast<const bf16x8*>(Qw + d0 * 16);
.LBB0_270:
	s_lshr_b32 s8, s4, 7
	s_sext_i32_i16 s0, s5
	v_cvt_f32_ubyte0_e32 v2, s8
	v_cvt_f32_i32_e32 v1, s0
	v_rcp_iflag_f32_e32 v3, v2
	s_ashr_i32 s0, s0, 30
	s_or_b32 s9, s0, 1
	v_mov_b32_e32 v38, v200
	v_mul_f32_e32 v3, v1, v3
	v_trunc_f32_e32 v3, v3
	v_fma_f32 v1, -v3, v2, v1
	v_cvt_i32_f32_e32 v3, v3
	v_cmp_ge_f32_e64 s[0:1], |v1|, v2
	s_and_b64 s[0:1], s[0:1], exec
	s_cselect_b32 s0, s9, 0
	v_readfirstlane_b32 s1, v3
	s_add_i32 s0, s1, s0
	s_sext_i32_i16 s1, s0
	s_mul_i32 s0, s0, s8
	s_sub_i32 s0, s5, s0
	s_sext_i32_i16 s0, s0
	s_lshl_b32 s5, s0, 7
	s_lshl_b32 s0, s1, 7
	v_readfirstlane_b32 s28, v38
	s_ashr_i32 s26, s28, 6
	s_ashr_i32 s1, s0, 31
	s_and_b32 s29, s26, 3
	s_and_b32 s27, s28, 0xffffffc0
	s_lshl_b64 s[0:1], s[0:1], 1
	v_lshlrev_b32_e32 v2, 3, v38
	s_add_u32 s8, s20, s0
	v_and_b32_e32 v114, 24, v2
	v_mov_b32_e32 v2, s28
	s_movk_i32 s47, 0xffc0
	s_addc_u32 s9, s21, s1
	v_bfi_b32 v115, s47, v2, v38
	v_and_b32_e32 v1, 15, v38
	s_add_u32 s18, s22, s0
	v_ashrrev_i32_e32 v2, 4, v115
	v_lshrrev_b32_e32 v8, 2, v38
	s_addc_u32 s19, s23, s1
	v_bitop3_b32 v4, v2, v1, 15 bitop3:0x6c
	s_ashr_i32 s47, s28, 4
	v_ashrrev_i32_e32 v3, 31, v2
	v_lshlrev_b32_e32 v52, 4, v4
	v_bfi_b32 v4, -8, s47, v8
	v_lshl_add_u64 v[2:3], s[2:3], 0, v[2:3]
	v_ashrrev_i32_e32 v5, 31, v4
	v_lshlrev_b64 v[50:51], 11, v[2:3]
	v_lshl_add_u64 v[4:5], s[2:3], 0, v[4:5]
	v_and_b32_e32 v188, 63, v38
	v_lshl_add_u64 v[2:3], s[8:9], 0, v[50:51]
	v_mov_b32_e32 v53, v0
	v_and_or_b32 v6, v115, s62, v114
	v_lshlrev_b64 v[54:55], 11, v[4:5]
	s_addk_i32 s27, 0x200
	v_lshl_add_u64 v[2:3], v[2:3], 0, v[52:53]
	v_lshl_add_u64 v[4:5], s[18:19], 0, v[54:55]
	v_lshlrev_b32_e32 v6, 1, v6
	v_mov_b32_e32 v7, v0
	v_or_b32_e32 v53, s27, v188
	v_lshl_add_u64 v[4:5], v[4:5], 0, v[6:7]
	v_ashrrev_i32_e32 v6, 4, v53
	v_ashrrev_i32_e32 v7, 31, v6
	v_bitop3_b32 v1, v6, v1, 15 bitop3:0x6c
	v_lshl_add_u64 v[6:7], s[2:3], 0, v[6:7]
	v_lshlrev_b64 v[56:57], 11, v[6:7]
	v_lshl_add_u64 v[6:7], s[8:9], 0, v[56:57]
	s_ashr_i32 s8, s27, 4
	v_bfi_b32 v8, -8, s8, v8
	s_lshl_b32 s8, s26, 10
	v_ashrrev_i32_e32 v9, 31, v8
	s_add_i32 s49, s8, 0
	v_mov_b32_e32 v18, v0
	v_mov_b32_e32 v19, v0
	v_mov_b32_e32 v20, v0
	v_mov_b32_e32 v21, v0
	v_mov_b32_e32 v22, v0
	v_mov_b32_e32 v23, v0
	v_mov_b32_e32 v24, v0
	v_mov_b32_e32 v25, v0
	v_mov_b32_e32 v26, v0
	v_mov_b32_e32 v27, v0
	v_mov_b32_e32 v28, v0
	v_mov_b32_e32 v29, v0
	v_mov_b32_e32 v30, v0
	v_mov_b32_e32 v31, v0
	v_mov_b32_e32 v32, v0
	v_mov_b32_e32 v33, v0
	v_lshlrev_b32_e32 v58, 4, v1
	v_mov_b32_e32 v59, v0
	v_lshl_add_u64 v[8:9], s[2:3], 0, v[8:9]
	s_mov_b32 m0, s49
	v_lshl_add_u64 v[6:7], v[6:7], 0, v[58:59]
	v_and_or_b32 v1, v53, s62, v114
	v_lshlrev_b64 v[60:61], 11, v[8:9]
	global_load_lds_dwordx4 v[2:3], off
	s_add_i32 m0, s49, 0x2000
	v_lshl_add_u64 v[8:9], s[18:19], 0, v[60:61]
	v_lshlrev_b32_e32 v10, 1, v1
	v_mov_b32_e32 v11, v0
	global_load_lds_dwordx4 v[6:7], off
	v_lshl_add_u64 v[8:9], v[8:9], 0, v[10:11]
	s_ashr_i32 s47, s28, 8
	s_ashr_i32 s8, s5, 31
	s_add_u32 s2, s2, s5
	s_addc_u32 s3, s3, s8
	s_lshl_b32 s5, s29, 5
	s_add_u32 s2, s5, s2
	v_and_b32_e32 v34, 31, v38
	v_mov_b32_e32 v35, v0
	s_addc_u32 s3, 0, s3
	v_lshl_add_u64 v[10:11], s[2:3], 0, v[34:35]
	v_lshlrev_b64 v[10:11], 11, v[10:11]
	v_lshl_add_u64 v[10:11], s[10:11], 0, v[10:11]
	s_lshl_b32 s2, s47, 6
	v_bfe_u32 v17, v38, 5, 1
	v_lshl_add_u64 v[166:167], v[10:11], 0, s[0:1]
	s_ashr_i32 s3, s2, 31
	v_lshl_add_u64 v[10:11], s[2:3], 1, v[166:167]
	v_lshlrev_b32_e32 v36, 4, v17
	v_mov_b32_e32 v37, v0
	v_lshl_add_u64 v[10:11], v[10:11], 0, v[36:37]
	global_load_dwordx4 v[158:161], v[10:11], off
	global_load_dwordx4 v[154:157], v[10:11], off offset:32
	global_load_dwordx4 v[150:153], v[10:11], off offset:64
	global_load_dwordx4 v[146:149], v[10:11], off offset:96
	s_add_i32 m0, s49, 0xc000
	s_nop 0
	global_load_lds_dwordx4 v[4:5], off
	s_add_i32 m0, s49, 0xe000
	s_nop 0
	global_load_lds_dwordx4 v[8:9], off
	v_lshl_add_u64 v[10:11], v[2:3], 0, s[40:41]
	s_add_i32 m0, s49, 0x4000
	s_nop 0
	global_load_lds_dwordx4 v[10:11], off
	v_lshl_add_u64 v[10:11], v[6:7], 0, s[40:41]
	s_add_i32 m0, s49, 0x6000
	s_nop 0
	global_load_lds_dwordx4 v[10:11], off
	s_waitcnt vmcnt(4) lgkmcnt(0)
	s_barrier
; __device__ __forceinline__ int v_rd_base(int lane) { return ((lane & 3) << 3) | (((lane >> 2) & 3) << 6) | (((lane >> 4) & 1) << 5) | (((lane >> 5) & 1) << 8); }
; #define WAIT_BAR(N) asm volatile("s_waitcnt vmcnt(" #N ") lgkmcnt(0)\n\ts_barrier" ::: "memory")
; #define DMA_K(t, slot) do { _Pragma("unroll") for (int i_ = 0; i_ < 2; ++i_) __builtin_amdgcn_global_load_lds((const unsigned*)(ksrc[i_] + (size_t)(t) * 64 * DM), (LAS unsigned*)(lds3 + (slot) + (i_ * 8 + wid) * 1024), 16, 0, 0); } while (0)
; #define DMA_V(t, slot) do { _Pragma("unroll") for (int i_ = 0; i_ < 2; ++i_) __builtin_amdgcn_global_load_lds((const unsigned*)(vsrc[i_] + (size_t)(t) * 64 * DM), (LAS unsigned*)(lds3 + RING + (slot) + (i_ * 8 + wid) * 1024), 16, 0, 0); } while (0)
; #define ROT() do { const int t_ = sl_prev; sl_prev = sl_cur; sl_cur = sl_next; sl_next = t_; } while (0)
; __device__ __forceinline__ void attnB_unit(const bf16* Q, const bf16* __restrict__ K, const bf16* __restrict__ V, bf16* O, long rowbase, int seq, int h, int q0, float lam, char* lds, LAS unsigned char* lds3) {
;     ...
;     const int vb0 = (int)(uintptr_t)V_lds + v_rd_base(lane);
;     ...
;     f32x16 pA0, pA1, pB0, pB1; float alA, alB; bf16x8 pa0, pa1, pa2, pa3; const int NT = seq / 64; const int colb0 = c * 128;
;     int sl_prev = 2 * SHM_KV, sl_cur = 0, sl_next = SHM_KV;
;     ...
;     WAIT_BAR(0);
;     DMA_K(2, sl_prev); DMA_V(1, sl_next);
;     qkt64n<256>(pA0, pA1, K_lds + sl_cur, qr, r32, hi, colb0, negm); partialSM2<true>(pA0, pA1, m_ref, alA, negm);
;     WAIT_BAR(4); ROT();
	s_add_i32 m0, s49, 0x8000
	v_lshl_add_u64 v[2:3], v[2:3], 0, s[86:87]
	s_lshr_b32 s50, s4, 6
	global_load_lds_dwordx4 v[2:3], off
	s_add_i32 m0, s49, 0xa000
	v_lshl_add_u64 v[2:3], v[6:7], 0, s[86:87]
	s_cmp_lg_u32 0, -1
	global_load_lds_dwordx4 v[2:3], off
	s_cselect_b32 s3, 0, 0
	s_add_i32 m0, s49, 0x10000
	v_lshl_add_u64 v[2:3], v[4:5], 0, s[40:41]
	global_load_lds_dwordx4 v[2:3], off
	v_lshl_add_u64 v[2:3], v[8:9], 0, s[40:41]
	s_add_i32 m0, s49, 0x12000
	v_lshlrev_b32_e32 v37, 4, v38
	global_load_lds_dwordx4 v[2:3], off
	v_lshlrev_b32_e32 v35, 3, v188
	v_and_b32_e32 v39, 0xc0, v37
	v_lshlrev_b32_e32 v38, 1, v38
	v_and_or_b32 v39, v35, 24, v39
	v_and_b32_e32 v38, 32, v38
	v_and_b32_e32 v35, 0x100, v35
	v_or3_b32 v35, v39, v38, v35
	s_add_i32 s3, s3, 0xc000
	v_add_u32_e32 v189, s3, v35
	s_lshl_b32 s3, s47, 7
	v_lshlrev_b32_e32 v191, 8, v34
	v_and_b32_e32 v59, 0xf0, v37
	v_add_u32_e32 v194, 0, v191
	v_or_b32_e32 v78, s3, v36
	v_bitop3_b32 v192, s3, v59, v36 bitop3:0x36
	v_add_u32_e32 v34, v194, v192
	v_bitop3_b32 v193, v78, v59, 32 bitop3:0x36
	ds_read_b128 v[62:65], v34
	ds_read_b128 v[66:69], v34 offset:8192
	v_add_u32_e32 v34, v194, v193
	ds_read_b128 v[70:73], v34
	ds_read_b128 v[74:77], v34 offset:8192
	s_waitcnt lgkmcnt(0)
	s_mov_b32 s2, 0
	s_mov_b32 s52, 4
	s_movk_i32 s51, 0x4000
	s_mov_b32 s48, 0x8000
	v_mov_b32_e32 v1, v0
	v_mov_b32_e32 v2, v0
	v_mov_b32_e32 v3, v0
	v_mov_b32_e32 v4, v0
	v_mov_b32_e32 v5, v0
	v_mov_b32_e32 v6, v0
	v_mov_b32_e32 v7, v0
	v_mov_b32_e32 v8, v0
	v_mov_b32_e32 v9, v0
	v_mov_b32_e32 v10, v0
	v_mov_b32_e32 v11, v0
	v_mov_b32_e32 v12, v0
	v_mov_b32_e32 v13, v0
	v_mov_b32_e32 v14, v0
	v_mov_b32_e32 v15, v0
	s_waitcnt vmcnt(8) lgkmcnt(0)
	v_mfma_f32_32x32x16_bf16 v[34:49], v[62:65], v[158:161], v[18:33]
	v_bitop3_b32 v190, v78, v59, 64 bitop3:0x36
	v_bitop3_b32 v195, v78, v59, s62 bitop3:0x36
	v_add_u32_e32 v59, v194, v195
	v_mfma_f32_32x32x16_bf16 v[18:33], v[66:69], v[158:161], v[18:33]
	v_add_u32_e32 v66, v194, v190
	ds_read_b128 v[62:65], v66
	ds_read_b128 v[66:69], v66 offset:8192
	v_mfma_f32_32x32x16_bf16 v[34:49], v[70:73], v[154:157], v[34:49]
	ds_read_b128 v[70:73], v59
	ds_read_b128 v[78:81], v59 offset:8192
	s_waitcnt lgkmcnt(0)
	v_mfma_f32_32x32x16_bf16 v[18:33], v[74:77], v[154:157], v[18:33]
	s_waitcnt lgkmcnt(3)
	v_mfma_f32_32x32x16_bf16 v[34:49], v[62:65], v[150:153], v[34:49]
	v_or_b32_e32 v56, v56, v58
	v_or_b32_e32 v50, v50, v52
	v_lshl_add_u64 v[172:173], s[14:15], 0, v[56:57]
	v_lshl_add_u64 v[174:175], s[14:15], 0, v[50:51]
	v_mov_b32_e32 v196, 0
	s_waitcnt lgkmcnt(1)
	v_mfma_f32_32x32x16_bf16 v[34:49], v[70:73], v[146:149], v[34:49]
	v_mfma_f32_32x32x16_bf16 v[18:33], v[66:69], v[150:153], v[18:33]
	s_nop 10
	v_max_f32_e32 v59, v35, v35
	v_max_f32_e32 v62, v34, v34
	v_max_f32_e32 v59, v62, v59
	v_max3_f32 v59, v59, v36, v37
	v_max3_f32 v59, v59, v38, v39
	v_max3_f32 v59, v59, v40, v41
	v_max3_f32 v59, v59, v42, v43
	s_waitcnt lgkmcnt(0)
	v_mfma_f32_32x32x16_bf16 v[18:33], v[78:81], v[146:149], v[18:33]
	v_max3_f32 v59, v59, v44, v45
	v_max3_f32 v59, v59, v46, v47
	v_max3_f32 v59, v59, v48, v49
	v_mov_b64_e32 v[80:81], v[14:15]
	v_mov_b64_e32 v[78:79], v[12:13]
	v_mov_b64_e32 v[76:77], v[10:11]
	v_mov_b64_e32 v[74:75], v[8:9]
	s_nop 4
	v_max3_f32 v59, v59, v18, v19
	v_max3_f32 v59, v59, v20, v21
	v_max3_f32 v59, v59, v22, v23
	v_max3_f32 v59, v59, v24, v25
	v_max3_f32 v59, v59, v26, v27
	v_max3_f32 v59, v59, v28, v29
	v_max3_f32 v59, v59, v30, v31
	v_max3_f32 v59, v59, v32, v33
	v_mov_b32_e32 v62, v59
	s_nop 1
	v_permlane32_swap_b32_e32 v59, v62
	v_max_f32_e32 v62, v62, v62
	v_max_f32_e32 v59, v59, v59
	v_max_f32_e32 v59, v59, v62
	v_sub_f32_e32 v98, v18, v59
	v_sub_f32_e32 v18, v34, v59
	v_exp_f32_e32 v212, v18
	v_sub_f32_e32 v18, v35, v59
	v_exp_f32_e32 v216, v18
	v_sub_f32_e32 v18, v36, v59
	v_exp_f32_e32 v213, v18
	v_sub_f32_e32 v18, v37, v59
	v_exp_f32_e32 v217, v18
	v_sub_f32_e32 v18, v38, v59
	v_exp_f32_e32 v214, v18
	v_sub_f32_e32 v18, v39, v59
	v_exp_f32_e32 v218, v18
	v_sub_f32_e32 v18, v40, v59
	v_exp_f32_e32 v215, v18
	v_sub_f32_e32 v18, v41, v59
	v_exp_f32_e32 v219, v18
	v_sub_f32_e32 v18, v42, v59
	v_exp_f32_e32 v197, v18
	v_sub_f32_e32 v18, v43, v59
	v_exp_f32_e32 v208, v18
	v_sub_f32_e32 v18, v44, v59
	v_exp_f32_e32 v198, v18
	v_sub_f32_e32 v18, v45, v59
	v_exp_f32_e32 v209, v18
	v_sub_f32_e32 v18, v46, v59
	v_exp_f32_e32 v199, v18
	v_sub_f32_e32 v18, v47, v59
	v_exp_f32_e32 v210, v18
	v_sub_f32_e32 v18, v48, v59
	v_exp_f32_e32 v207, v18
	v_sub_f32_e32 v18, v49, v59
	v_exp_f32_e32 v211, v18
	v_lshlrev_b32_e32 v18, 1, v115
	v_add_f32_e32 v162, 0, v59
	v_sub_f32_e32 v99, v19, v59
	v_and_b32_e32 v18, 0xc0, v18
	v_lshlrev_b32_e32 v19, 1, v114
	v_xor_b32_e32 v82, 0x80000000, v162
	v_or3_b32 v54, v18, v19, v54
	v_lshlrev_b32_e32 v18, 1, v53
	v_mov_b32_e32 v83, v82
	v_mov_b32_e32 v84, v82
	v_mov_b32_e32 v85, v82
	v_mov_b32_e32 v86, v82
	v_mov_b32_e32 v87, v82
	v_mov_b32_e32 v88, v82
	v_mov_b32_e32 v89, v82
	v_mov_b32_e32 v90, v82
	v_mov_b32_e32 v91, v82
	v_mov_b32_e32 v92, v82
	v_mov_b32_e32 v93, v82
	v_mov_b32_e32 v94, v82
	v_mov_b32_e32 v95, v82
	v_mov_b32_e32 v96, v82
	v_mov_b32_e32 v97, v82
	v_and_b32_e32 v18, 0xc0, v18
	s_waitcnt vmcnt(4) lgkmcnt(0)
	s_barrier
	s_cmp_eq_u32 s47, 0
	s_cbranch_scc1 .Lprio_skip
	s_setprio 1
.Lprio_skip:
	v_or3_b32 v60, v18, v19, v60
	v_sub_f32_e32 v113, v33, v59
	v_sub_f32_e32 v112, v32, v59
	v_sub_f32_e32 v111, v31, v59
	v_sub_f32_e32 v110, v30, v59
	v_sub_f32_e32 v109, v29, v59
	v_sub_f32_e32 v108, v28, v59
	v_sub_f32_e32 v107, v27, v59
	v_sub_f32_e32 v106, v26, v59
	v_sub_f32_e32 v105, v25, v59
	v_sub_f32_e32 v104, v24, v59
	v_sub_f32_e32 v103, v23, v59
	v_sub_f32_e32 v102, v22, v59
	v_sub_f32_e32 v101, v21, v59
	v_sub_f32_e32 v100, v20, v59
	v_lshl_add_u64 v[168:169], s[14:15], 0, v[54:55]
	v_lshl_add_u64 v[170:171], s[14:15], 0, v[60:61]
	v_mov_b64_e32 v[64:65], v[14:15]
	v_mov_b64_e32 v[48:49], v[14:15]
	v_mov_b64_e32 v[32:33], v[14:15]
	v_mov_b64_e32 v[72:73], v[6:7]
	v_mov_b64_e32 v[70:71], v[4:5]
	v_mov_b64_e32 v[68:69], v[2:3]
	v_mov_b64_e32 v[66:67], v[0:1]
	v_mov_b64_e32 v[62:63], v[12:13]
	v_mov_b64_e32 v[60:61], v[10:11]
	v_mov_b64_e32 v[58:59], v[8:9]
	v_mov_b64_e32 v[56:57], v[6:7]
	v_mov_b64_e32 v[54:55], v[4:5]
	v_mov_b64_e32 v[52:53], v[2:3]
	v_mov_b64_e32 v[50:51], v[0:1]
	v_mov_b64_e32 v[46:47], v[12:13]
	v_mov_b64_e32 v[44:45], v[10:11]
	v_mov_b64_e32 v[42:43], v[8:9]
	v_mov_b64_e32 v[40:41], v[6:7]
	v_mov_b64_e32 v[38:39], v[4:5]
	v_mov_b64_e32 v[36:37], v[2:3]
	v_mov_b64_e32 v[34:35], v[0:1]
	v_mov_b64_e32 v[30:31], v[12:13]
	v_mov_b64_e32 v[28:29], v[10:11]
	v_mov_b64_e32 v[26:27], v[8:9]
	v_mov_b64_e32 v[24:25], v[6:7]
	v_mov_b64_e32 v[22:23], v[4:5]
	v_mov_b64_e32 v[20:21], v[2:3]
	v_mov_b64_e32 v[18:19], v[0:1]

; #define SBAR() __builtin_amdgcn_sched_barrier(0)
; #define WAIT_BAR(N) asm volatile("s_waitcnt vmcnt(" #N ") lgkmcnt(0)\n\ts_barrier" ::: "memory")
; #define PV5(vb) do { pv_ksT<0>(o, vb, pa0); pv_ksT<1>(o, vb, pa1); pv_ksT<2>(o, vb, pa2); pv_ksT<3>(o, vb, pa3); } while (0)
; __device__ __forceinline__ void attnB_unit(const bf16* Q, const bf16* __restrict__ K, const bf16* __restrict__ V, bf16* O, long rowbase, int seq, int h, int q0, float lam, char* lds, LAS unsigned char* lds3) {
;     ...
;     WAIT_BAR(0);
;     finishSM2T(pB0, pB1, l_reg, pa0, pa1, pa2, pa3); SBAR();
;     PV5(vb0 + sl_cur);
;     const float rl = __builtin_amdgcn_rcpf(l_reg);
;     __syncthreads();
.LBB0_302:
	v_exp_f32_e32 v2, v114
	v_exp_f32_e32 v4, v115
	v_exp_f32_e32 v5, v116
	v_exp_f32_e32 v6, v117
	v_exp_f32_e32 v7, v118
	v_add_f32_e32 v101, 0, v2
	v_exp_f32_e32 v8, v119
	v_add_f32_e32 v101, v4, v101
	v_exp_f32_e32 v9, v120
	v_add_f32_e32 v101, v5, v101
	v_exp_f32_e32 v10, v121
	v_add_f32_e32 v101, v6, v101
	v_exp_f32_e32 v11, v122
	v_add_f32_e32 v101, v7, v101
	v_exp_f32_e32 v12, v123
	v_add_f32_e32 v101, v8, v101
	v_exp_f32_e32 v13, v124
	v_add_f32_e32 v101, v9, v101
	v_exp_f32_e32 v14, v125
	v_add_f32_e32 v101, v10, v101
	v_exp_f32_e32 v15, v126
	v_add_f32_e32 v101, v11, v101
	v_exp_f32_e32 v98, v127
	v_add_f32_e32 v101, v12, v101
	v_exp_f32_e32 v99, v128
	v_add_f32_e32 v101, v13, v101
	v_exp_f32_e32 v100, v129
	v_add_f32_e32 v101, v14, v101
	v_exp_f32_e32 v82, v82
	v_add_f32_e32 v101, v15, v101
	v_exp_f32_e32 v83, v83
	v_add_f32_e32 v101, v98, v101
	v_exp_f32_e32 v84, v84
	v_add_f32_e32 v101, v99, v101
	v_exp_f32_e32 v85, v85
	v_add_f32_e32 v101, v100, v101
	v_exp_f32_e32 v86, v86
	v_add_f32_e32 v101, v82, v101
	v_exp_f32_e32 v87, v87
	v_add_f32_e32 v101, v83, v101
	v_exp_f32_e32 v88, v88
	v_add_f32_e32 v101, v84, v101
	v_exp_f32_e32 v89, v89
	v_add_f32_e32 v101, v85, v101
	v_exp_f32_e32 v90, v90
	v_add_f32_e32 v101, v86, v101
	v_exp_f32_e32 v91, v91
	v_add_f32_e32 v101, v87, v101
	v_exp_f32_e32 v92, v92
	v_add_f32_e32 v101, v88, v101
	v_exp_f32_e32 v93, v93
	v_add_f32_e32 v101, v89, v101
	v_exp_f32_e32 v94, v94
	v_add_f32_e32 v101, v90, v101
	v_exp_f32_e32 v95, v95
	v_add_f32_e32 v101, v91, v101
	v_exp_f32_e32 v96, v96
	v_add_f32_e32 v101, v92, v101
	v_exp_f32_e32 v97, v97
	v_add_f32_e32 v101, v93, v101
	v_add_f32_e32 v101, v94, v101
	v_add_f32_e32 v101, v95, v101
	v_add_f32_e32 v101, v96, v101
	v_add_f32_e32 v101, v97, v101
	s_waitcnt vmcnt(0) lgkmcnt(0)
	s_barrier
	v_mov_b32_e32 v102, v101
	s_nop 1
	v_permlane32_swap_b32_e32 v101, v102
	v_add_f32_e32 v101, v101, v102
	v_add_f32_e32 v102, v3, v101
	v_cvt_pk_bf16_f32 v2, v2, v4
	v_cvt_pk_bf16_f32 v3, v5, v6
	v_cvt_pk_bf16_f32 v4, v7, v8
	v_cvt_pk_bf16_f32 v5, v9, v10
	v_cvt_pk_bf16_f32 v6, v11, v12
	v_cvt_pk_bf16_f32 v7, v13, v14
	v_cvt_pk_bf16_f32 v8, v15, v98
	v_cvt_pk_bf16_f32 v9, v99, v100
	v_cvt_pk_bf16_f32 v10, v82, v83
	v_cvt_pk_bf16_f32 v11, v84, v85
	v_cvt_pk_bf16_f32 v12, v86, v87
	v_cvt_pk_bf16_f32 v13, v88, v89
	v_cvt_pk_bf16_f32 v82, v90, v91
	v_cvt_pk_bf16_f32 v83, v92, v93
	v_cvt_pk_bf16_f32 v84, v94, v95
	v_cvt_pk_bf16_f32 v85, v96, v97
	ds_read_b64_tr_b16 v[86:87], v1 offset:0
	ds_read_b64_tr_b16 v[88:89], v1 offset:0x800
	ds_read_b64_tr_b16 v[90:91], v1 offset:0x200
	ds_read_b64_tr_b16 v[92:93], v1 offset:0xa00
	ds_read_b64_tr_b16 v[94:95], v1 offset:0x400
	ds_read_b64_tr_b16 v[96:97], v1 offset:0xc00
	ds_read_b64_tr_b16 v[98:99], v1 offset:0x600
	ds_read_b64_tr_b16 v[100:101], v1 offset:0xe00
	s_waitcnt lgkmcnt(0)
	s_nop 0
	v_mfma_f32_32x32x16_bf16 v[66:81], v[86:89], v[2:5], v[66:81]
	v_mfma_f32_32x32x16_bf16 v[50:65], v[90:93], v[2:5], v[50:65]
	v_mfma_f32_32x32x16_bf16 v[34:49], v[94:97], v[2:5], v[34:49]
	v_mfma_f32_32x32x16_bf16 v[18:33], v[98:101], v[2:5], v[18:33]
	ds_read_b64_tr_b16 v[2:3], v1 offset:0x1000
	ds_read_b64_tr_b16 v[4:5], v1 offset:0x1800
	ds_read_b64_tr_b16 v[86:87], v1 offset:0x1200
	ds_read_b64_tr_b16 v[88:89], v1 offset:0x1a00
	ds_read_b64_tr_b16 v[90:91], v1 offset:0x1400
	ds_read_b64_tr_b16 v[92:93], v1 offset:0x1c00
	ds_read_b64_tr_b16 v[94:95], v1 offset:0x1600
	ds_read_b64_tr_b16 v[96:97], v1 offset:0x1e00
	s_waitcnt lgkmcnt(0)
	s_nop 0
	v_mfma_f32_32x32x16_bf16 v[66:81], v[2:5], v[6:9], v[66:81]
	ds_read_b64_tr_b16 v[2:3], v1 offset:0x2000
	ds_read_b64_tr_b16 v[4:5], v1 offset:0x2800
	v_mfma_f32_32x32x16_bf16 v[50:65], v[86:89], v[6:9], v[50:65]
	v_mfma_f32_32x32x16_bf16 v[34:49], v[90:93], v[6:9], v[34:49]
	v_mfma_f32_32x32x16_bf16 v[18:33], v[94:97], v[6:9], v[18:33]
	ds_read_b64_tr_b16 v[6:7], v1 offset:0x2200
	ds_read_b64_tr_b16 v[8:9], v1 offset:0x2a00
	ds_read_b64_tr_b16 v[86:87], v1 offset:0x2400
	ds_read_b64_tr_b16 v[88:89], v1 offset:0x2c00
	ds_read_b64_tr_b16 v[90:91], v1 offset:0x2600
	ds_read_b64_tr_b16 v[92:93], v1 offset:0x2e00
	s_waitcnt lgkmcnt(0)
	v_mfma_f32_32x32x16_bf16 v[66:81], v[2:5], v[10:13], v[66:81]
	ds_read_b64_tr_b16 v[2:3], v1 offset:0x3000
	ds_read_b64_tr_b16 v[4:5], v1 offset:0x3800
	v_mfma_f32_32x32x16_bf16 v[50:65], v[6:9], v[10:13], v[50:65]
	ds_read_b64_tr_b16 v[6:7], v1 offset:0x3200
	ds_read_b64_tr_b16 v[8:9], v1 offset:0x3a00
	v_mfma_f32_32x32x16_bf16 v[34:49], v[86:89], v[10:13], v[34:49]
	v_mfma_f32_32x32x16_bf16 v[18:33], v[90:93], v[10:13], v[18:33]
	ds_read_b64_tr_b16 v[10:11], v1 offset:0x3400
	ds_read_b64_tr_b16 v[12:13], v1 offset:0x3c00
	ds_read_b64_tr_b16 v[86:87], v1 offset:0x3600
	ds_read_b64_tr_b16 v[88:89], v1 offset:0x3e00
	s_waitcnt lgkmcnt(0)
	v_mfma_f32_32x32x16_bf16 v[66:81], v[2:5], v[82:85], v[66:81]
	v_rcp_f32_e32 v162, v102
	s_lshl_b32 s0, s29, 14
	s_add_i32 s0, s0, 0
	v_lshl_add_u32 v1, v188, 2, s0
	s_setprio 0
	s_cmp_lg_u32 s47, 1
	s_waitcnt vmcnt(0)
	s_barrier
; __device__ __forceinline__ void attnB_unit(const bf16* Q, const bf16* __restrict__ K, const bf16* __restrict__ V, bf16* O, long rowbase, int seq, int h, int q0, float lam, char* lds, LAS unsigned char* lds3) {
;     ...
;     float* X = (float*)lds + wq * 4096 + lane;
;     if (c == 1) {
; #pragma unroll
;         for (int d0 = 0; d0 < 4; ++d0)
; #pragma unroll
;             for (int r = 0; r < 16; ++r) X[(d0 * 16 + r) * 64] = o[d0][r] * rl;
;     }
	v_mfma_f32_32x32x16_bf16 v[50:65], v[6:9], v[82:85], v[50:65]
	v_mfma_f32_32x32x16_bf16 v[34:49], v[10:13], v[82:85], v[34:49]
	v_mfma_f32_32x32x16_bf16 v[18:33], v[86:89], v[82:85], v[18:33]
	s_cbranch_scc1 .LBB0_304
	s_nop 0
	v_mul_f32_e32 v2, v162, v66
	v_mul_f32_e32 v3, v162, v67
	ds_write2st64_b32 v1, v2, v3 offset1:1
	v_mul_f32_e32 v2, v162, v68
	v_mul_f32_e32 v3, v162, v69
	ds_write2st64_b32 v1, v2, v3 offset0:2 offset1:3
	v_mul_f32_e32 v2, v162, v70
	v_mul_f32_e32 v3, v162, v71
	ds_write2st64_b32 v1, v2, v3 offset0:4 offset1:5
	v_mul_f32_e32 v2, v162, v72
	v_mul_f32_e32 v3, v162, v73
	ds_write2st64_b32 v1, v2, v3 offset0:6 offset1:7
	v_mul_f32_e32 v2, v162, v74
	v_mul_f32_e32 v3, v162, v75
	ds_write2st64_b32 v1, v2, v3 offset0:8 offset1:9
	v_mul_f32_e32 v2, v162, v76
	v_mul_f32_e32 v3, v162, v77
	ds_write2st64_b32 v1, v2, v3 offset0:10 offset1:11
	v_mul_f32_e32 v2, v162, v78
	v_mul_f32_e32 v3, v162, v79
	ds_write2st64_b32 v1, v2, v3 offset0:12 offset1:13
	v_mul_f32_e32 v2, v162, v80
	v_mul_f32_e32 v3, v162, v81
	ds_write2st64_b32 v1, v2, v3 offset0:14 offset1:15
	v_mul_f32_e32 v2, v162, v50
	v_mul_f32_e32 v3, v162, v51
	ds_write2st64_b32 v1, v2, v3 offset0:16 offset1:17
	v_mul_f32_e32 v2, v162, v52
	v_mul_f32_e32 v3, v162, v53
	ds_write2st64_b32 v1, v2, v3 offset0:18 offset1:19
	v_mul_f32_e32 v2, v162, v54
	v_mul_f32_e32 v3, v162, v55
	ds_write2st64_b32 v1, v2, v3 offset0:20 offset1:21
	v_mul_f32_e32 v2, v162, v56
	v_mul_f32_e32 v3, v162, v57
	ds_write2st64_b32 v1, v2, v3 offset0:22 offset1:23
	v_mul_f32_e32 v2, v162, v58
	v_mul_f32_e32 v3, v162, v59
	ds_write2st64_b32 v1, v2, v3 offset0:24 offset1:25
	v_mul_f32_e32 v2, v162, v60
	v_mul_f32_e32 v3, v162, v61
	ds_write2st64_b32 v1, v2, v3 offset0:26 offset1:27
	v_mul_f32_e32 v2, v162, v62
	v_mul_f32_e32 v3, v162, v63
	ds_write2st64_b32 v1, v2, v3 offset0:28 offset1:29
	v_mul_f32_e32 v2, v162, v64
	v_mul_f32_e32 v3, v162, v65
	ds_write2st64_b32 v1, v2, v3 offset0:30 offset1:31
	v_mul_f32_e32 v2, v162, v34
	v_mul_f32_e32 v3, v162, v35
	ds_write2st64_b32 v1, v2, v3 offset0:32 offset1:33
	v_mul_f32_e32 v2, v162, v36
	v_mul_f32_e32 v3, v162, v37
	ds_write2st64_b32 v1, v2, v3 offset0:34 offset1:35
	v_mul_f32_e32 v2, v162, v38
	v_mul_f32_e32 v3, v162, v39
	ds_write2st64_b32 v1, v2, v3 offset0:36 offset1:37
	v_mul_f32_e32 v2, v162, v40
	v_mul_f32_e32 v3, v162, v41
	ds_write2st64_b32 v1, v2, v3 offset0:38 offset1:39
	v_mul_f32_e32 v2, v162, v42
	v_mul_f32_e32 v3, v162, v43
	ds_write2st64_b32 v1, v2, v3 offset0:40 offset1:41
	v_mul_f32_e32 v2, v162, v44
	v_mul_f32_e32 v3, v162, v45
	ds_write2st64_b32 v1, v2, v3 offset0:42 offset1:43
	v_mul_f32_e32 v2, v162, v46
	v_mul_f32_e32 v3, v162, v47
	ds_write2st64_b32 v1, v2, v3 offset0:44 offset1:45
	v_mul_f32_e32 v2, v162, v48
	v_mul_f32_e32 v3, v162, v49
	ds_write2st64_b32 v1, v2, v3 offset0:46 offset1:47
	v_mul_f32_e32 v2, v162, v18
	v_mul_f32_e32 v3, v162, v19
	ds_write2st64_b32 v1, v2, v3 offset0:48 offset1:49
	v_mul_f32_e32 v2, v162, v20
	v_mul_f32_e32 v3, v162, v21
	ds_write2st64_b32 v1, v2, v3 offset0:50 offset1:51
	v_mul_f32_e32 v2, v162, v22
	v_mul_f32_e32 v3, v162, v23
	ds_write2st64_b32 v1, v2, v3 offset0:52 offset1:53
	v_mul_f32_e32 v2, v162, v24
	v_mul_f32_e32 v3, v162, v25
	ds_write2st64_b32 v1, v2, v3 offset0:54 offset1:55
	v_mul_f32_e32 v2, v162, v26
	v_mul_f32_e32 v3, v162, v27
	ds_write2st64_b32 v1, v2, v3 offset0:56 offset1:57
	v_mul_f32_e32 v2, v162, v28
	v_mul_f32_e32 v3, v162, v29
	ds_write2st64_b32 v1, v2, v3 offset0:58 offset1:59
	v_mul_f32_e32 v2, v162, v30
	v_mul_f32_e32 v3, v162, v31
	ds_write2st64_b32 v1, v2, v3 offset0:60 offset1:61
	v_mul_f32_e32 v2, v162, v32
	v_mul_f32_e32 v3, v162, v33
	ds_write2st64_b32 v1, v2, v3 offset0:62 offset1:63
